# gate-weight rows of w_in (conversion tiles 1408..2175, first read two grid barriers later) moved out of phase 0 / the layer-1 re-conversion into the in-projection start slot of the 5-tile workgroups,
# speedup vs baseline: 1.0173x; 1.0049x over previous
.Lxmap_ok:
.LBB0_17:
	s_or_b64 exec, exec, s[0:1]
	s_mov_b64 s[0:1], 0
	s_add_u32 s6, s96, s0
	s_addc_u32 s7, s97, s1
	v_mov_b32_e32 v48, v197
	v_mov_b32_e32 v10, v197
	s_cmpk_gt_i32 s52, 0x57f
	s_cbranch_scc1 .LBB0_78
	s_cmpk_lt_i32 s52, 0x880
	s_cselect_b64 s[0:1], -1, 0
	s_cmpk_gt_i32 s52, 0x87f
	s_cbranch_scc0 .LBB0_20
	s_add_i32 s3, s52, 0xfffff780
	v_readlane_b32 s8, v253, 0
	s_cmpk_lt_u32 s3, 0x200
	s_mov_b32 s4, 0x10100000
	v_readlane_b32 s9, v253, 1
	v_readlane_b32 s12, v253, 4
	v_readlane_b32 s13, v253, 5
	v_readlane_b32 s14, v253, 6
	v_readlane_b32 s15, v253, 7
	s_cselect_b32 s4, s4, 0x10500000
	s_cselect_b32 s5, s13, s15
	s_cselect_b32 s8, s12, s14
	s_lshl_b32 s9, s3, 12
	v_readlane_b32 s10, v253, 2
	s_and_b32 s9, s9, 0x100000
	s_lshl_b32 s10, s9, 2
	s_add_u32 s12, s8, s10
	s_addc_u32 s13, s5, 0
	s_add_u32 s4, s6, s4
	s_addc_u32 s5, s7, 0
	s_lshl_b32 s8, s9, 1
	s_add_u32 s4, s4, s8
	v_readlane_b32 s11, v253, 3
	s_addc_u32 s5, s5, 0
	s_lshl_b32 s3, s3, 2
	s_and_b32 s8, s3, 0x3c0
	s_lshl_b32 s3, s52, 2
	s_mov_b64 s[14:15], 0x400
	s_mov_b32 s11, s8
	s_cbranch_execz .LBB0_21
	s_branch .LBB0_37

.LBB0_40:
	s_add_i32 s47, s47, s98
	s_cmpk_gt_i32 s47, 0x57f
	s_cselect_b64 s[16:17], -1, 0
	s_and_b64 vcc, exec, s[16:17]
	s_waitcnt vmcnt(1)
	ds_write2_b32 v15, v0, v1 offset1:1
	ds_write2_b32 v15, v2, v3 offset0:2 offset1:3
	s_waitcnt vmcnt(0)
	ds_write2_b32 v18, v4, v5 offset1:1
	ds_write2_b32 v19, v6, v7 offset1:1
	s_waitcnt lgkmcnt(0)
	s_barrier
	s_cbranch_vccnz .LBB0_59
	s_cmpk_lt_i32 s47, 0x880
	s_cselect_b64 s[14:15], -1, 0
	s_cmpk_gt_i32 s47, 0x87f
	s_mov_b64 s[26:27], -1
	s_cbranch_scc0 .LBB0_43
	s_add_i32 s18, s47, 0xfffff780
	v_readlane_b32 s20, v253, 0
	s_cmpk_lt_u32 s18, 0x200
	v_readlane_b32 s21, v253, 1
	v_readlane_b32 s24, v253, 4
	v_readlane_b32 s25, v253, 5
	v_readlane_b32 s26, v253, 6
	v_readlane_b32 s27, v253, 7
	s_cselect_b32 s18, s39, 0x10500000
	v_readlane_b32 s22, v253, 2
	s_cselect_b32 s19, s25, s27
	s_cselect_b32 s20, s24, s26
	s_and_b32 s21, s33, 0x100000
	s_lshl_b32 s22, s21, 2
	v_readlane_b32 s23, v253, 3
	s_add_u32 s22, s20, s22
	s_addc_u32 s23, s19, 0
	s_add_u32 s18, s6, s18
	s_addc_u32 s19, s7, 0
	s_lshl_b32 s20, s21, 1
	s_add_u32 s20, s18, s20
	s_addc_u32 s21, s19, 0
	s_add_i32 s18, s9, s3
	s_addk_i32 s18, 0xde00
	s_and_b32 s18, s18, 0x3c0
	s_mov_b64 s[26:27], 0

.LBB0_241:
	s_or_b64 exec, exec, s[0:1]
	v_readlane_b32 s2, v253, 26
	v_readlane_b32 s3, v253, 27
	s_mov_b64 s[0:1], 0
	s_andn2_b64 vcc, exec, s[2:3]
	s_waitcnt lgkmcnt(0)
	s_barrier
	s_cbranch_vccnz .LBB0_243
	v_lshrrev_b32_e32 v120, 4, v197
	v_and_b32_e32 v121, 15, v197
	v_lshlrev_b32_e32 v121, 2, v121
	v_lshl_add_u32 v122, v120, 10, v121
	v_lshlrev_b32_e32 v122, 2, v122
	v_mul_u32_u24_e32 v138, 0x8800, v120
	v_lshl_add_u32 v138, v121, 2, v138
	v_mul_u32_u24_e32 v123, 0x41, v120
	v_add_u32_e32 v123, v123, v121
	v_lshlrev_b32_e32 v123, 2, v123
	v_lshrrev_b32_e32 v124, 3, v197
	v_and_b32_e32 v125, 7, v197
	v_lshlrev_b32_e32 v125, 3, v125
	v_bfe_u32 v127, v124, 2, 2
	v_lshlrev_b32_e32 v127, 3, v127
	v_bfe_u32 v136, v124, 4, 1
	v_lshl_add_u32 v127, v136, 2, v127
	v_and_b32_e32 v136, 3, v124
	v_add_u32_e32 v127, v127, v136
	v_and_b32_e32 v136, 32, v124
	v_add_u32_e32 v127, v127, v136
	v_mul_u32_u24_e32 v136, 0x41, v125
	v_add_u32_e32 v136, v136, v127
	v_lshlrev_b32_e32 v136, 2, v136
	v_lshl_add_u32 v137, v124, 10, v125
	v_lshlrev_b32_e32 v137, 1, v137
	s_sub_i32 s2, s52, 0x80
	v_readlane_b32 s3, v252, 23
	s_nop 3
	s_cmp_eq_u32 s3, 0
	s_cbranch_scc1 .Lcw_l1
	v_readlane_b32 s28, v253, 4
	v_readlane_b32 s29, v253, 5
	v_readlane_b32 s30, v253, 6
	v_readlane_b32 s31, v253, 7
	s_nop 3
	s_add_i32 s4, s2, 0
	s_cmpk_lt_u32 s4, 0x200
	s_cselect_b32 s6, s28, s30
	s_cselect_b32 s7, s29, s31
	s_mov_b32 s16, 0x10500000
	s_cselect_b32 s16, 0x10100000, s16
	s_bfe_u32 s5, s4, 0x10008
	s_lshl_b32 s3, s5, 22
	s_add_u32 s6, s6, s3
	s_addc_u32 s7, s7, 0
	s_lshl_b32 s3, s5, 21
	s_add_i32 s16, s16, s3
	s_and_b32 s3, s4, 15
	s_bfe_u32 s5, s4, 0x40004
	s_lshl_b32 s17, s3, 18
	s_lshl_b32 s20, s5, 8
	s_add_i32 s17, s17, s20
	s_add_u32 s6, s6, s17
	s_addc_u32 s7, s7, 0
	s_add_u32 s12, s6, 0x20000
	s_addc_u32 s13, s7, 0
	s_lshl_b32 s17, s5, 17
	s_lshl_b32 s20, s3, 7
	s_add_i32 s17, s17, s20
	s_add_i32 s16, s16, s17
	s_add_u32 s16, s96, s16
	s_addc_u32 s17, s97, 0
	global_load_dwordx4 v[140:143], v122, s[6:7]
	global_load_dwordx4 v[150:153], v122, s[12:13]
	s_waitcnt vmcnt(0)
	ds_write_b32 v123, v140 offset:0
	ds_write_b32 v123, v141 offset:4
	ds_write_b32 v123, v142 offset:8
	ds_write_b32 v123, v143 offset:12
	ds_write_b32 v123, v150 offset:8320
	ds_write_b32 v123, v151 offset:8324
	ds_write_b32 v123, v152 offset:8328
	ds_write_b32 v123, v153 offset:8332
	s_waitcnt lgkmcnt(0)
	s_barrier
	s_mov_b64 s[26:27], s[16:17]
	s_add_i32 s4, s2, 128
	s_cmpk_lt_u32 s4, 0x200
	s_cselect_b32 s6, s28, s30
	s_cselect_b32 s7, s29, s31
	s_mov_b32 s16, 0x10500000
	s_cselect_b32 s16, 0x10100000, s16
	s_bfe_u32 s5, s4, 0x10008
	s_lshl_b32 s3, s5, 22
	s_add_u32 s6, s6, s3
	s_addc_u32 s7, s7, 0
	s_lshl_b32 s3, s5, 21
	s_add_i32 s16, s16, s3
	s_and_b32 s3, s4, 15
	s_bfe_u32 s5, s4, 0x40004
	s_lshl_b32 s17, s3, 18
	s_lshl_b32 s20, s5, 8
	s_add_i32 s17, s17, s20
	s_add_u32 s6, s6, s17
	s_addc_u32 s7, s7, 0
	s_add_u32 s12, s6, 0x20000
	s_addc_u32 s13, s7, 0
	s_lshl_b32 s17, s5, 17
	s_lshl_b32 s20, s3, 7
	s_add_i32 s17, s17, s20
	s_add_i32 s16, s16, s17
	s_add_u32 s16, s96, s16
	s_addc_u32 s17, s97, 0
	global_load_dwordx4 v[140:143], v122, s[6:7]
	global_load_dwordx4 v[150:153], v122, s[12:13]
	ds_read_b32 v154, v136 offset:0
	ds_read_b32 v155, v136 offset:260
	ds_read_b32 v156, v136 offset:520
	ds_read_b32 v157, v136 offset:780
	ds_read_b32 v158, v136 offset:1040
	ds_read_b32 v159, v136 offset:1300
	ds_read_b32 v160, v136 offset:1560
	ds_read_b32 v161, v136 offset:1820
	s_waitcnt lgkmcnt(0)
	v_cvt_pk_bf16_f32 v204, v154, v155
	v_cvt_pk_bf16_f32 v205, v156, v157
	v_cvt_pk_bf16_f32 v206, v158, v159
	v_cvt_pk_bf16_f32 v207, v160, v161
	global_store_dwordx4 v137, v[204:207], s[26:27]
	s_barrier
	s_waitcnt vmcnt(0)
	ds_write_b32 v123, v140 offset:0
	ds_write_b32 v123, v141 offset:4
	ds_write_b32 v123, v142 offset:8
	ds_write_b32 v123, v143 offset:12
	ds_write_b32 v123, v150 offset:8320
	ds_write_b32 v123, v151 offset:8324
	ds_write_b32 v123, v152 offset:8328
	ds_write_b32 v123, v153 offset:8332
	s_waitcnt lgkmcnt(0)
	s_barrier
	s_mov_b64 s[26:27], s[16:17]
	s_add_i32 s4, s2, 256
	s_cmpk_lt_u32 s4, 0x200
	s_cselect_b32 s6, s28, s30
	s_cselect_b32 s7, s29, s31
	s_mov_b32 s16, 0x10500000
	s_cselect_b32 s16, 0x10100000, s16
	s_bfe_u32 s5, s4, 0x10008
	s_lshl_b32 s3, s5, 22
	s_add_u32 s6, s6, s3
	s_addc_u32 s7, s7, 0
	s_lshl_b32 s3, s5, 21
	s_add_i32 s16, s16, s3
	s_and_b32 s3, s4, 15
	s_bfe_u32 s5, s4, 0x40004
	s_lshl_b32 s17, s3, 18
	s_lshl_b32 s20, s5, 8
	s_add_i32 s17, s17, s20
	s_add_u32 s6, s6, s17
	s_addc_u32 s7, s7, 0
	s_add_u32 s12, s6, 0x20000
	s_addc_u32 s13, s7, 0
	s_lshl_b32 s17, s5, 17
	s_lshl_b32 s20, s3, 7
	s_add_i32 s17, s17, s20
	s_add_i32 s16, s16, s17
	s_add_u32 s16, s96, s16
	s_addc_u32 s17, s97, 0
	global_load_dwordx4 v[140:143], v122, s[6:7]
	global_load_dwordx4 v[150:153], v122, s[12:13]
	ds_read_b32 v154, v136 offset:0
	ds_read_b32 v155, v136 offset:260
	ds_read_b32 v156, v136 offset:520
	ds_read_b32 v157, v136 offset:780
	ds_read_b32 v158, v136 offset:1040
	ds_read_b32 v159, v136 offset:1300
	ds_read_b32 v160, v136 offset:1560
	ds_read_b32 v161, v136 offset:1820
	s_waitcnt lgkmcnt(0)
	v_cvt_pk_bf16_f32 v204, v154, v155
	v_cvt_pk_bf16_f32 v205, v156, v157
	v_cvt_pk_bf16_f32 v206, v158, v159
	v_cvt_pk_bf16_f32 v207, v160, v161
	global_store_dwordx4 v137, v[204:207], s[26:27]
	s_barrier
	s_waitcnt vmcnt(0)
	ds_write_b32 v123, v140 offset:0
	ds_write_b32 v123, v141 offset:4
	ds_write_b32 v123, v142 offset:8
	ds_write_b32 v123, v143 offset:12
	ds_write_b32 v123, v150 offset:8320
	ds_write_b32 v123, v151 offset:8324
	ds_write_b32 v123, v152 offset:8328
	ds_write_b32 v123, v153 offset:8332
	s_waitcnt lgkmcnt(0)
	s_barrier
	s_mov_b64 s[26:27], s[16:17]
	s_add_i32 s4, s2, 384
	s_cmpk_lt_u32 s4, 0x200
	s_cselect_b32 s6, s28, s30
	s_cselect_b32 s7, s29, s31
	s_mov_b32 s16, 0x10500000
	s_cselect_b32 s16, 0x10100000, s16
	s_bfe_u32 s5, s4, 0x10008
	s_lshl_b32 s3, s5, 22
	s_add_u32 s6, s6, s3
	s_addc_u32 s7, s7, 0
	s_lshl_b32 s3, s5, 21
	s_add_i32 s16, s16, s3
	s_and_b32 s3, s4, 15
	s_bfe_u32 s5, s4, 0x40004
	s_lshl_b32 s17, s3, 18
	s_lshl_b32 s20, s5, 8
	s_add_i32 s17, s17, s20
	s_add_u32 s6, s6, s17
	s_addc_u32 s7, s7, 0
	s_add_u32 s12, s6, 0x20000
	s_addc_u32 s13, s7, 0
	s_lshl_b32 s17, s5, 17
	s_lshl_b32 s20, s3, 7
	s_add_i32 s17, s17, s20
	s_add_i32 s16, s16, s17
	s_add_u32 s16, s96, s16
	s_addc_u32 s17, s97, 0
	global_load_dwordx4 v[140:143], v122, s[6:7]
	global_load_dwordx4 v[150:153], v122, s[12:13]
	ds_read_b32 v154, v136 offset:0
	ds_read_b32 v155, v136 offset:260
	ds_read_b32 v156, v136 offset:520
	ds_read_b32 v157, v136 offset:780
	ds_read_b32 v158, v136 offset:1040
	ds_read_b32 v159, v136 offset:1300
	ds_read_b32 v160, v136 offset:1560
	ds_read_b32 v161, v136 offset:1820
	s_waitcnt lgkmcnt(0)
	v_cvt_pk_bf16_f32 v204, v154, v155
	v_cvt_pk_bf16_f32 v205, v156, v157
	v_cvt_pk_bf16_f32 v206, v158, v159
	v_cvt_pk_bf16_f32 v207, v160, v161
	global_store_dwordx4 v137, v[204:207], s[26:27]
	s_barrier
	s_waitcnt vmcnt(0)
	ds_write_b32 v123, v140 offset:0
	ds_write_b32 v123, v141 offset:4
	ds_write_b32 v123, v142 offset:8
	ds_write_b32 v123, v143 offset:12
	ds_write_b32 v123, v150 offset:8320
	ds_write_b32 v123, v151 offset:8324
	ds_write_b32 v123, v152 offset:8328
	ds_write_b32 v123, v153 offset:8332
	s_waitcnt lgkmcnt(0)
	s_barrier
	s_mov_b64 s[26:27], s[16:17]
	s_add_i32 s4, s2, 512
	s_cmpk_lt_u32 s4, 0x200
	s_cselect_b32 s6, s28, s30
	s_cselect_b32 s7, s29, s31
	s_mov_b32 s16, 0x10500000
	s_cselect_b32 s16, 0x10100000, s16
	s_bfe_u32 s5, s4, 0x10008
	s_lshl_b32 s3, s5, 22
	s_add_u32 s6, s6, s3
	s_addc_u32 s7, s7, 0
	s_lshl_b32 s3, s5, 21
	s_add_i32 s16, s16, s3
	s_and_b32 s3, s4, 15
	s_bfe_u32 s5, s4, 0x40004
	s_lshl_b32 s17, s3, 18
	s_lshl_b32 s20, s5, 8
	s_add_i32 s17, s17, s20
	s_add_u32 s6, s6, s17
	s_addc_u32 s7, s7, 0
	s_add_u32 s12, s6, 0x20000
	s_addc_u32 s13, s7, 0
	s_lshl_b32 s17, s5, 17
	s_lshl_b32 s20, s3, 7
	s_add_i32 s17, s17, s20
	s_add_i32 s16, s16, s17
	s_add_u32 s16, s96, s16
	s_addc_u32 s17, s97, 0
	global_load_dwordx4 v[140:143], v122, s[6:7]
	global_load_dwordx4 v[150:153], v122, s[12:13]
	ds_read_b32 v154, v136 offset:0
	ds_read_b32 v155, v136 offset:260
	ds_read_b32 v156, v136 offset:520
	ds_read_b32 v157, v136 offset:780
	ds_read_b32 v158, v136 offset:1040
	ds_read_b32 v159, v136 offset:1300
	ds_read_b32 v160, v136 offset:1560
	ds_read_b32 v161, v136 offset:1820
	s_waitcnt lgkmcnt(0)
	v_cvt_pk_bf16_f32 v204, v154, v155
	v_cvt_pk_bf16_f32 v205, v156, v157
	v_cvt_pk_bf16_f32 v206, v158, v159
	v_cvt_pk_bf16_f32 v207, v160, v161
	global_store_dwordx4 v137, v[204:207], s[26:27]
	s_barrier
	s_waitcnt vmcnt(0)
	ds_write_b32 v123, v140 offset:0
	ds_write_b32 v123, v141 offset:4
	ds_write_b32 v123, v142 offset:8
	ds_write_b32 v123, v143 offset:12
	ds_write_b32 v123, v150 offset:8320
	ds_write_b32 v123, v151 offset:8324
	ds_write_b32 v123, v152 offset:8328
	ds_write_b32 v123, v153 offset:8332
	s_waitcnt lgkmcnt(0)
	s_barrier
	s_mov_b64 s[26:27], s[16:17]
	s_add_i32 s4, s2, 640
	s_cmpk_lt_u32 s4, 0x200
	s_cselect_b32 s6, s28, s30
	s_cselect_b32 s7, s29, s31
	s_mov_b32 s16, 0x10500000
	s_cselect_b32 s16, 0x10100000, s16
	s_bfe_u32 s5, s4, 0x10008
	s_lshl_b32 s3, s5, 22
	s_add_u32 s6, s6, s3
	s_addc_u32 s7, s7, 0
	s_lshl_b32 s3, s5, 21
	s_add_i32 s16, s16, s3
	s_and_b32 s3, s4, 15
	s_bfe_u32 s5, s4, 0x40004
	s_lshl_b32 s17, s3, 18
	s_lshl_b32 s20, s5, 8
	s_add_i32 s17, s17, s20
	s_add_u32 s6, s6, s17
	s_addc_u32 s7, s7, 0
	s_add_u32 s12, s6, 0x20000
	s_addc_u32 s13, s7, 0
	s_lshl_b32 s17, s5, 17
	s_lshl_b32 s20, s3, 7
	s_add_i32 s17, s17, s20
	s_add_i32 s16, s16, s17
	s_add_u32 s16, s96, s16
	s_addc_u32 s17, s97, 0
	global_load_dwordx4 v[140:143], v122, s[6:7]
	global_load_dwordx4 v[150:153], v122, s[12:13]
	ds_read_b32 v154, v136 offset:0
	ds_read_b32 v155, v136 offset:260
	ds_read_b32 v156, v136 offset:520
	ds_read_b32 v157, v136 offset:780
	ds_read_b32 v158, v136 offset:1040
	ds_read_b32 v159, v136 offset:1300
	ds_read_b32 v160, v136 offset:1560
	ds_read_b32 v161, v136 offset:1820
	s_waitcnt lgkmcnt(0)
	v_cvt_pk_bf16_f32 v204, v154, v155
	v_cvt_pk_bf16_f32 v205, v156, v157
	v_cvt_pk_bf16_f32 v206, v158, v159
	v_cvt_pk_bf16_f32 v207, v160, v161
	global_store_dwordx4 v137, v[204:207], s[26:27]
	s_barrier
	s_waitcnt vmcnt(0)
	ds_write_b32 v123, v140 offset:0
	ds_write_b32 v123, v141 offset:4
	ds_write_b32 v123, v142 offset:8
	ds_write_b32 v123, v143 offset:12
	ds_write_b32 v123, v150 offset:8320
	ds_write_b32 v123, v151 offset:8324
	ds_write_b32 v123, v152 offset:8328
	ds_write_b32 v123, v153 offset:8332
	s_waitcnt lgkmcnt(0)
	s_barrier
	s_mov_b64 s[26:27], s[16:17]
	s_add_i32 s4, s2, 768
	s_cmpk_lt_u32 s4, 0x200
	s_cselect_b32 s6, s28, s30
	s_cselect_b32 s7, s29, s31
	s_mov_b32 s16, 0x10500000
	s_cselect_b32 s16, 0x10100000, s16
	s_bfe_u32 s5, s4, 0x10008
	s_lshl_b32 s3, s5, 22
	s_add_u32 s6, s6, s3
	s_addc_u32 s7, s7, 0
	s_lshl_b32 s3, s5, 21
	s_add_i32 s16, s16, s3
	s_and_b32 s3, s4, 15
	s_bfe_u32 s5, s4, 0x40004
	s_lshl_b32 s17, s3, 18
	s_lshl_b32 s20, s5, 8
	s_add_i32 s17, s17, s20
	s_add_u32 s6, s6, s17
	s_addc_u32 s7, s7, 0
	s_add_u32 s12, s6, 0x20000
	s_addc_u32 s13, s7, 0
	s_lshl_b32 s17, s5, 17
	s_lshl_b32 s20, s3, 7
	s_add_i32 s17, s17, s20
	s_add_i32 s16, s16, s17
	s_add_u32 s16, s96, s16
	s_addc_u32 s17, s97, 0
	global_load_dwordx4 v[140:143], v122, s[6:7]
	global_load_dwordx4 v[150:153], v122, s[12:13]
	ds_read_b32 v154, v136 offset:0
	ds_read_b32 v155, v136 offset:260
	ds_read_b32 v156, v136 offset:520
	ds_read_b32 v157, v136 offset:780
	ds_read_b32 v158, v136 offset:1040
	ds_read_b32 v159, v136 offset:1300
	ds_read_b32 v160, v136 offset:1560
	ds_read_b32 v161, v136 offset:1820
	s_waitcnt lgkmcnt(0)
	v_cvt_pk_bf16_f32 v204, v154, v155
	v_cvt_pk_bf16_f32 v205, v156, v157
	v_cvt_pk_bf16_f32 v206, v158, v159
	v_cvt_pk_bf16_f32 v207, v160, v161
	global_store_dwordx4 v137, v[204:207], s[26:27]
	s_barrier
	s_waitcnt vmcnt(0)
	ds_write_b32 v123, v140 offset:0
	ds_write_b32 v123, v141 offset:4
	ds_write_b32 v123, v142 offset:8
	ds_write_b32 v123, v143 offset:12
	ds_write_b32 v123, v150 offset:8320
	ds_write_b32 v123, v151 offset:8324
	ds_write_b32 v123, v152 offset:8328
	ds_write_b32 v123, v153 offset:8332
	s_waitcnt lgkmcnt(0)
	s_barrier
	s_mov_b64 s[26:27], s[16:17]
	s_add_i32 s4, s2, 896
	s_cmpk_lt_u32 s4, 0x200
	s_cselect_b32 s6, s28, s30
	s_cselect_b32 s7, s29, s31
	s_mov_b32 s16, 0x10500000
	s_cselect_b32 s16, 0x10100000, s16
	s_bfe_u32 s5, s4, 0x10008
	s_lshl_b32 s3, s5, 22
	s_add_u32 s6, s6, s3
	s_addc_u32 s7, s7, 0
	s_lshl_b32 s3, s5, 21
	s_add_i32 s16, s16, s3
	s_and_b32 s3, s4, 15
	s_bfe_u32 s5, s4, 0x40004
	s_lshl_b32 s17, s3, 18
	s_lshl_b32 s20, s5, 8
	s_add_i32 s17, s17, s20
	s_add_u32 s6, s6, s17
	s_addc_u32 s7, s7, 0
	s_add_u32 s12, s6, 0x20000
	s_addc_u32 s13, s7, 0
	s_lshl_b32 s17, s5, 17
	s_lshl_b32 s20, s3, 7
	s_add_i32 s17, s17, s20
	s_add_i32 s16, s16, s17
	s_add_u32 s16, s96, s16
	s_addc_u32 s17, s97, 0
	global_load_dwordx4 v[140:143], v122, s[6:7]
	global_load_dwordx4 v[150:153], v122, s[12:13]
	ds_read_b32 v154, v136 offset:0
	ds_read_b32 v155, v136 offset:260
	ds_read_b32 v156, v136 offset:520
	ds_read_b32 v157, v136 offset:780
	ds_read_b32 v158, v136 offset:1040
	ds_read_b32 v159, v136 offset:1300
	ds_read_b32 v160, v136 offset:1560
	ds_read_b32 v161, v136 offset:1820
	s_waitcnt lgkmcnt(0)
	v_cvt_pk_bf16_f32 v204, v154, v155
	v_cvt_pk_bf16_f32 v205, v156, v157
	v_cvt_pk_bf16_f32 v206, v158, v159
	v_cvt_pk_bf16_f32 v207, v160, v161
	global_store_dwordx4 v137, v[204:207], s[26:27]
	s_barrier
	s_waitcnt vmcnt(0)
	ds_write_b32 v123, v140 offset:0
	ds_write_b32 v123, v141 offset:4
	ds_write_b32 v123, v142 offset:8
	ds_write_b32 v123, v143 offset:12
	ds_write_b32 v123, v150 offset:8320
	ds_write_b32 v123, v151 offset:8324
	ds_write_b32 v123, v152 offset:8328
	ds_write_b32 v123, v153 offset:8332
	s_waitcnt lgkmcnt(0)
	s_barrier
	s_mov_b64 s[26:27], s[16:17]
	ds_read_b32 v154, v136 offset:0
	ds_read_b32 v155, v136 offset:260
	ds_read_b32 v156, v136 offset:520
	ds_read_b32 v157, v136 offset:780
	ds_read_b32 v158, v136 offset:1040
	ds_read_b32 v159, v136 offset:1300
	ds_read_b32 v160, v136 offset:1560
	ds_read_b32 v161, v136 offset:1820
	s_waitcnt lgkmcnt(0)
	v_cvt_pk_bf16_f32 v204, v154, v155
	v_cvt_pk_bf16_f32 v205, v156, v157
	v_cvt_pk_bf16_f32 v206, v158, v159
	v_cvt_pk_bf16_f32 v207, v160, v161
	global_store_dwordx4 v137, v[204:207], s[26:27]
	s_barrier
	v_readlane_b32 s28, v253, 20
	v_readlane_b32 s29, v253, 21
	s_nop 3
	s_add_i32 s4, s2, 1408
	s_and_b32 s3, s4, 15
	s_lshr_b32 s5, s4, 4
	s_mul_i32 s17, s3, 0x220000
	s_lshl_b32 s20, s5, 8
	s_add_i32 s17, s17, s20
	s_add_u32 s6, s28, s17
	s_addc_u32 s7, s29, 0
	s_add_u32 s12, s6, 0x110000
	s_addc_u32 s13, s7, 0
	s_lshl_b32 s17, s5, 17
	s_lshl_b32 s20, s3, 7
	s_add_i32 s17, s17, s20
	s_add_u32 s16, s96, s17
	s_addc_u32 s17, s97, 0
	s_add_u32 s16, s16, 0xf000000
	s_addc_u32 s17, s17, 0
	global_load_dwordx4 v[140:143], v138, s[6:7]
	global_load_dwordx4 v[150:153], v138, s[12:13]
	s_waitcnt vmcnt(0)
	ds_write_b32 v123, v140 offset:0
	ds_write_b32 v123, v141 offset:4
	ds_write_b32 v123, v142 offset:8
	ds_write_b32 v123, v143 offset:12
	ds_write_b32 v123, v150 offset:8320
	ds_write_b32 v123, v151 offset:8324
	ds_write_b32 v123, v152 offset:8328
	ds_write_b32 v123, v153 offset:8332
	s_waitcnt lgkmcnt(0)
	s_barrier
	s_mov_b64 s[26:27], s[16:17]
	s_add_i32 s4, s2, 1536
	s_and_b32 s3, s4, 15
	s_lshr_b32 s5, s4, 4
	s_mul_i32 s17, s3, 0x220000
	s_lshl_b32 s20, s5, 8
	s_add_i32 s17, s17, s20
	s_add_u32 s6, s28, s17
	s_addc_u32 s7, s29, 0
	s_add_u32 s12, s6, 0x110000
	s_addc_u32 s13, s7, 0
	s_lshl_b32 s17, s5, 17
	s_lshl_b32 s20, s3, 7
	s_add_i32 s17, s17, s20
	s_add_u32 s16, s96, s17
	s_addc_u32 s17, s97, 0
	s_add_u32 s16, s16, 0xf000000
	s_addc_u32 s17, s17, 0
	global_load_dwordx4 v[140:143], v138, s[6:7]
	global_load_dwordx4 v[150:153], v138, s[12:13]
	ds_read_b32 v154, v136 offset:0
	ds_read_b32 v155, v136 offset:260
	ds_read_b32 v156, v136 offset:520
	ds_read_b32 v157, v136 offset:780
	ds_read_b32 v158, v136 offset:1040
	ds_read_b32 v159, v136 offset:1300
	ds_read_b32 v160, v136 offset:1560
	ds_read_b32 v161, v136 offset:1820
	s_waitcnt lgkmcnt(0)
	v_mul_f32_e32 v154, v235, v154
	v_mul_f32_e32 v155, v235, v155
	v_mul_f32_e32 v156, v235, v156
	v_mul_f32_e32 v157, v235, v157
	v_mul_f32_e32 v158, v235, v158
	v_mul_f32_e32 v159, v235, v159
	v_mul_f32_e32 v160, v235, v160
	v_mul_f32_e32 v161, v235, v161
	v_cvt_pk_bf16_f32 v204, v154, v155
	v_cvt_pk_bf16_f32 v205, v156, v157
	v_cvt_pk_bf16_f32 v206, v158, v159
	v_cvt_pk_bf16_f32 v207, v160, v161
	global_store_dwordx4 v137, v[204:207], s[26:27]
	s_barrier
	s_waitcnt vmcnt(0)
	ds_write_b32 v123, v140 offset:0
	ds_write_b32 v123, v141 offset:4
	ds_write_b32 v123, v142 offset:8
	ds_write_b32 v123, v143 offset:12
	ds_write_b32 v123, v150 offset:8320
	ds_write_b32 v123, v151 offset:8324
	ds_write_b32 v123, v152 offset:8328
	ds_write_b32 v123, v153 offset:8332
	s_waitcnt lgkmcnt(0)
	s_barrier
	s_mov_b64 s[26:27], s[16:17]
	s_add_i32 s4, s2, 1664
	s_and_b32 s3, s4, 15
	s_lshr_b32 s5, s4, 4
	s_mul_i32 s17, s3, 0x220000
	s_lshl_b32 s20, s5, 8
	s_add_i32 s17, s17, s20
	s_add_u32 s6, s28, s17
	s_addc_u32 s7, s29, 0
	s_add_u32 s12, s6, 0x110000
	s_addc_u32 s13, s7, 0
	s_lshl_b32 s17, s5, 17
	s_lshl_b32 s20, s3, 7
	s_add_i32 s17, s17, s20
	s_add_u32 s16, s96, s17
	s_addc_u32 s17, s97, 0
	s_add_u32 s16, s16, 0xf000000
	s_addc_u32 s17, s17, 0
	global_load_dwordx4 v[140:143], v138, s[6:7]
	global_load_dwordx4 v[150:153], v138, s[12:13]
	ds_read_b32 v154, v136 offset:0
	ds_read_b32 v155, v136 offset:260
	ds_read_b32 v156, v136 offset:520
	ds_read_b32 v157, v136 offset:780
	ds_read_b32 v158, v136 offset:1040
	ds_read_b32 v159, v136 offset:1300
	ds_read_b32 v160, v136 offset:1560
	ds_read_b32 v161, v136 offset:1820
	s_waitcnt lgkmcnt(0)
	v_mul_f32_e32 v154, v235, v154
	v_mul_f32_e32 v155, v235, v155
	v_mul_f32_e32 v156, v235, v156
	v_mul_f32_e32 v157, v235, v157
	v_mul_f32_e32 v158, v235, v158
	v_mul_f32_e32 v159, v235, v159
	v_mul_f32_e32 v160, v235, v160
	v_mul_f32_e32 v161, v235, v161
	v_cvt_pk_bf16_f32 v204, v154, v155
	v_cvt_pk_bf16_f32 v205, v156, v157
	v_cvt_pk_bf16_f32 v206, v158, v159
	v_cvt_pk_bf16_f32 v207, v160, v161
	global_store_dwordx4 v137, v[204:207], s[26:27]
	s_barrier
	s_waitcnt vmcnt(0)
	ds_write_b32 v123, v140 offset:0
	ds_write_b32 v123, v141 offset:4
	ds_write_b32 v123, v142 offset:8
	ds_write_b32 v123, v143 offset:12
	ds_write_b32 v123, v150 offset:8320
	ds_write_b32 v123, v151 offset:8324
	ds_write_b32 v123, v152 offset:8328
	ds_write_b32 v123, v153 offset:8332
	s_waitcnt lgkmcnt(0)
	s_barrier
	s_mov_b64 s[26:27], s[16:17]
	s_add_i32 s4, s2, 1792
	s_and_b32 s3, s4, 15
	s_lshr_b32 s5, s4, 4
	s_mul_i32 s17, s3, 0x220000
	s_lshl_b32 s20, s5, 8
	s_add_i32 s17, s17, s20
	s_add_u32 s6, s28, s17
	s_addc_u32 s7, s29, 0
	s_add_u32 s12, s6, 0x110000
	s_addc_u32 s13, s7, 0
	s_lshl_b32 s17, s5, 17
	s_lshl_b32 s20, s3, 7
	s_add_i32 s17, s17, s20
	s_add_u32 s16, s96, s17
	s_addc_u32 s17, s97, 0
	s_add_u32 s16, s16, 0xf000000
	s_addc_u32 s17, s17, 0
	global_load_dwordx4 v[140:143], v138, s[6:7]
	global_load_dwordx4 v[150:153], v138, s[12:13]
	ds_read_b32 v154, v136 offset:0
	ds_read_b32 v155, v136 offset:260
	ds_read_b32 v156, v136 offset:520
	ds_read_b32 v157, v136 offset:780
	ds_read_b32 v158, v136 offset:1040
	ds_read_b32 v159, v136 offset:1300
	ds_read_b32 v160, v136 offset:1560
	ds_read_b32 v161, v136 offset:1820
	s_waitcnt lgkmcnt(0)
	v_mul_f32_e32 v154, v235, v154
	v_mul_f32_e32 v155, v235, v155
	v_mul_f32_e32 v156, v235, v156
	v_mul_f32_e32 v157, v235, v157
	v_mul_f32_e32 v158, v235, v158
	v_mul_f32_e32 v159, v235, v159
	v_mul_f32_e32 v160, v235, v160
	v_mul_f32_e32 v161, v235, v161
	v_cvt_pk_bf16_f32 v204, v154, v155
	v_cvt_pk_bf16_f32 v205, v156, v157
	v_cvt_pk_bf16_f32 v206, v158, v159
	v_cvt_pk_bf16_f32 v207, v160, v161
	global_store_dwordx4 v137, v[204:207], s[26:27]
	s_barrier
	s_waitcnt vmcnt(0)
	ds_write_b32 v123, v140 offset:0
	ds_write_b32 v123, v141 offset:4
	ds_write_b32 v123, v142 offset:8
	ds_write_b32 v123, v143 offset:12
	ds_write_b32 v123, v150 offset:8320
	ds_write_b32 v123, v151 offset:8324
	ds_write_b32 v123, v152 offset:8328
	ds_write_b32 v123, v153 offset:8332
	s_waitcnt lgkmcnt(0)
	s_barrier
	s_mov_b64 s[26:27], s[16:17]
	s_add_i32 s4, s2, 1920
	s_and_b32 s3, s4, 15
	s_lshr_b32 s5, s4, 4
	s_mul_i32 s17, s3, 0x220000
	s_lshl_b32 s20, s5, 8
	s_add_i32 s17, s17, s20
	s_add_u32 s6, s28, s17
	s_addc_u32 s7, s29, 0
	s_add_u32 s12, s6, 0x110000
	s_addc_u32 s13, s7, 0
	s_lshl_b32 s17, s5, 17
	s_lshl_b32 s20, s3, 7
	s_add_i32 s17, s17, s20
	s_add_u32 s16, s96, s17
	s_addc_u32 s17, s97, 0
	s_add_u32 s16, s16, 0xf000000
	s_addc_u32 s17, s17, 0
	global_load_dwordx4 v[140:143], v138, s[6:7]
	global_load_dwordx4 v[150:153], v138, s[12:13]
	ds_read_b32 v154, v136 offset:0
	ds_read_b32 v155, v136 offset:260
	ds_read_b32 v156, v136 offset:520
	ds_read_b32 v157, v136 offset:780
	ds_read_b32 v158, v136 offset:1040
	ds_read_b32 v159, v136 offset:1300
	ds_read_b32 v160, v136 offset:1560
	ds_read_b32 v161, v136 offset:1820
	s_waitcnt lgkmcnt(0)
	v_mul_f32_e32 v154, v235, v154
	v_mul_f32_e32 v155, v235, v155
	v_mul_f32_e32 v156, v235, v156
	v_mul_f32_e32 v157, v235, v157
	v_mul_f32_e32 v158, v235, v158
	v_mul_f32_e32 v159, v235, v159
	v_mul_f32_e32 v160, v235, v160
	v_mul_f32_e32 v161, v235, v161
	v_cvt_pk_bf16_f32 v204, v154, v155
	v_cvt_pk_bf16_f32 v205, v156, v157
	v_cvt_pk_bf16_f32 v206, v158, v159
	v_cvt_pk_bf16_f32 v207, v160, v161
	global_store_dwordx4 v137, v[204:207], s[26:27]
	s_barrier
	s_waitcnt vmcnt(0)
	ds_write_b32 v123, v140 offset:0
	ds_write_b32 v123, v141 offset:4
	ds_write_b32 v123, v142 offset:8
	ds_write_b32 v123, v143 offset:12
	ds_write_b32 v123, v150 offset:8320
	ds_write_b32 v123, v151 offset:8324
	ds_write_b32 v123, v152 offset:8328
	ds_write_b32 v123, v153 offset:8332
	s_waitcnt lgkmcnt(0)
	s_barrier
	s_mov_b64 s[26:27], s[16:17]
	s_add_i32 s4, s2, 2048
	s_and_b32 s3, s4, 15
	s_lshr_b32 s5, s4, 4
	s_mul_i32 s17, s3, 0x220000
	s_lshl_b32 s20, s5, 8
	s_add_i32 s17, s17, s20
	s_add_u32 s6, s28, s17
	s_addc_u32 s7, s29, 0
	s_add_u32 s12, s6, 0x110000
	s_addc_u32 s13, s7, 0
	s_lshl_b32 s17, s5, 17
	s_lshl_b32 s20, s3, 7
	s_add_i32 s17, s17, s20
	s_add_u32 s16, s96, s17
	s_addc_u32 s17, s97, 0
	s_add_u32 s16, s16, 0xf000000
	s_addc_u32 s17, s17, 0
	global_load_dwordx4 v[140:143], v138, s[6:7]
	global_load_dwordx4 v[150:153], v138, s[12:13]
	ds_read_b32 v154, v136 offset:0
	ds_read_b32 v155, v136 offset:260
	ds_read_b32 v156, v136 offset:520
	ds_read_b32 v157, v136 offset:780
	ds_read_b32 v158, v136 offset:1040
	ds_read_b32 v159, v136 offset:1300
	ds_read_b32 v160, v136 offset:1560
	ds_read_b32 v161, v136 offset:1820
	s_waitcnt lgkmcnt(0)
	v_mul_f32_e32 v154, v235, v154
	v_mul_f32_e32 v155, v235, v155
	v_mul_f32_e32 v156, v235, v156
	v_mul_f32_e32 v157, v235, v157
	v_mul_f32_e32 v158, v235, v158
	v_mul_f32_e32 v159, v235, v159
	v_mul_f32_e32 v160, v235, v160
	v_mul_f32_e32 v161, v235, v161
	v_cvt_pk_bf16_f32 v204, v154, v155
	v_cvt_pk_bf16_f32 v205, v156, v157
	v_cvt_pk_bf16_f32 v206, v158, v159
	v_cvt_pk_bf16_f32 v207, v160, v161
	global_store_dwordx4 v137, v[204:207], s[26:27]
	s_barrier
	s_waitcnt vmcnt(0)
	ds_write_b32 v123, v140 offset:0
	ds_write_b32 v123, v141 offset:4
	ds_write_b32 v123, v142 offset:8
	ds_write_b32 v123, v143 offset:12
	ds_write_b32 v123, v150 offset:8320
	ds_write_b32 v123, v151 offset:8324
	ds_write_b32 v123, v152 offset:8328
	ds_write_b32 v123, v153 offset:8332
	s_waitcnt lgkmcnt(0)
	s_barrier
	s_mov_b64 s[26:27], s[16:17]
	ds_read_b32 v154, v136 offset:0
	ds_read_b32 v155, v136 offset:260
	ds_read_b32 v156, v136 offset:520
	ds_read_b32 v157, v136 offset:780
	ds_read_b32 v158, v136 offset:1040
	ds_read_b32 v159, v136 offset:1300
	ds_read_b32 v160, v136 offset:1560
	ds_read_b32 v161, v136 offset:1820
	s_waitcnt lgkmcnt(0)
	v_mul_f32_e32 v154, v235, v154
	v_mul_f32_e32 v155, v235, v155
	v_mul_f32_e32 v156, v235, v156
	v_mul_f32_e32 v157, v235, v157
	v_mul_f32_e32 v158, v235, v158
	v_mul_f32_e32 v159, v235, v159
	v_mul_f32_e32 v160, v235, v160
	v_mul_f32_e32 v161, v235, v161
	v_cvt_pk_bf16_f32 v204, v154, v155
	v_cvt_pk_bf16_f32 v205, v156, v157
	v_cvt_pk_bf16_f32 v206, v158, v159
	v_cvt_pk_bf16_f32 v207, v160, v161
	global_store_dwordx4 v137, v[204:207], s[26:27]
	s_barrier
	s_branch .LBB0_243
.Lcw_l1:
	v_readlane_b32 s28, v253, 20
	v_readlane_b32 s29, v253, 21
	s_nop 3
	s_add_u32 s28, s28, 0x2200000
	s_addc_u32 s29, s29, 0
	s_add_i32 s4, s2, 1408
	s_and_b32 s3, s4, 15
	s_lshr_b32 s5, s4, 4
	s_mul_i32 s17, s3, 0x220000
	s_lshl_b32 s20, s5, 8
	s_add_i32 s17, s17, s20
	s_add_u32 s6, s28, s17
	s_addc_u32 s7, s29, 0
	s_add_u32 s12, s6, 0x110000
	s_addc_u32 s13, s7, 0
	s_lshl_b32 s17, s5, 17
	s_lshl_b32 s20, s3, 7
	s_add_i32 s17, s17, s20
	s_add_u32 s16, s96, s17
	s_addc_u32 s17, s97, 0
	s_add_u32 s16, s16, 0xf000000
	s_addc_u32 s17, s17, 0
	global_load_dwordx4 v[140:143], v138, s[6:7]
	global_load_dwordx4 v[150:153], v138, s[12:13]
	s_waitcnt vmcnt(0)
	ds_write_b32 v123, v140 offset:0
	ds_write_b32 v123, v141 offset:4
	ds_write_b32 v123, v142 offset:8
	ds_write_b32 v123, v143 offset:12
	ds_write_b32 v123, v150 offset:8320
	ds_write_b32 v123, v151 offset:8324
	ds_write_b32 v123, v152 offset:8328
	ds_write_b32 v123, v153 offset:8332
	s_waitcnt lgkmcnt(0)
	s_barrier
	s_mov_b64 s[26:27], s[16:17]
	s_add_i32 s4, s2, 1536
	s_and_b32 s3, s4, 15
	s_lshr_b32 s5, s4, 4
	s_mul_i32 s17, s3, 0x220000
	s_lshl_b32 s20, s5, 8
	s_add_i32 s17, s17, s20
	s_add_u32 s6, s28, s17
	s_addc_u32 s7, s29, 0
	s_add_u32 s12, s6, 0x110000
	s_addc_u32 s13, s7, 0
	s_lshl_b32 s17, s5, 17
	s_lshl_b32 s20, s3, 7
	s_add_i32 s17, s17, s20
	s_add_u32 s16, s96, s17
	s_addc_u32 s17, s97, 0
	s_add_u32 s16, s16, 0xf000000
	s_addc_u32 s17, s17, 0
	global_load_dwordx4 v[140:143], v138, s[6:7]
	global_load_dwordx4 v[150:153], v138, s[12:13]
	ds_read_b32 v154, v136 offset:0
	ds_read_b32 v155, v136 offset:260
	ds_read_b32 v156, v136 offset:520
	ds_read_b32 v157, v136 offset:780
	ds_read_b32 v158, v136 offset:1040
	ds_read_b32 v159, v136 offset:1300
	ds_read_b32 v160, v136 offset:1560
	ds_read_b32 v161, v136 offset:1820
	s_waitcnt lgkmcnt(0)
	v_mul_f32_e32 v154, v235, v154
	v_mul_f32_e32 v155, v235, v155
	v_mul_f32_e32 v156, v235, v156
	v_mul_f32_e32 v157, v235, v157
	v_mul_f32_e32 v158, v235, v158
	v_mul_f32_e32 v159, v235, v159
	v_mul_f32_e32 v160, v235, v160
	v_mul_f32_e32 v161, v235, v161
	v_cvt_pk_bf16_f32 v204, v154, v155
	v_cvt_pk_bf16_f32 v205, v156, v157
	v_cvt_pk_bf16_f32 v206, v158, v159
	v_cvt_pk_bf16_f32 v207, v160, v161
	global_store_dwordx4 v137, v[204:207], s[26:27]
	s_barrier
	s_waitcnt vmcnt(0)
	ds_write_b32 v123, v140 offset:0
	ds_write_b32 v123, v141 offset:4
	ds_write_b32 v123, v142 offset:8
	ds_write_b32 v123, v143 offset:12
	ds_write_b32 v123, v150 offset:8320
	ds_write_b32 v123, v151 offset:8324
	ds_write_b32 v123, v152 offset:8328
	ds_write_b32 v123, v153 offset:8332
	s_waitcnt lgkmcnt(0)
	s_barrier
	s_mov_b64 s[26:27], s[16:17]
	s_add_i32 s4, s2, 1664
	s_and_b32 s3, s4, 15
	s_lshr_b32 s5, s4, 4
	s_mul_i32 s17, s3, 0x220000
	s_lshl_b32 s20, s5, 8
	s_add_i32 s17, s17, s20
	s_add_u32 s6, s28, s17
	s_addc_u32 s7, s29, 0
	s_add_u32 s12, s6, 0x110000
	s_addc_u32 s13, s7, 0
	s_lshl_b32 s17, s5, 17
	s_lshl_b32 s20, s3, 7
	s_add_i32 s17, s17, s20
	s_add_u32 s16, s96, s17
	s_addc_u32 s17, s97, 0
	s_add_u32 s16, s16, 0xf000000
	s_addc_u32 s17, s17, 0
	global_load_dwordx4 v[140:143], v138, s[6:7]
	global_load_dwordx4 v[150:153], v138, s[12:13]
	ds_read_b32 v154, v136 offset:0
	ds_read_b32 v155, v136 offset:260
	ds_read_b32 v156, v136 offset:520
	ds_read_b32 v157, v136 offset:780
	ds_read_b32 v158, v136 offset:1040
	ds_read_b32 v159, v136 offset:1300
	ds_read_b32 v160, v136 offset:1560
	ds_read_b32 v161, v136 offset:1820
	s_waitcnt lgkmcnt(0)
	v_mul_f32_e32 v154, v235, v154
	v_mul_f32_e32 v155, v235, v155
	v_mul_f32_e32 v156, v235, v156
	v_mul_f32_e32 v157, v235, v157
	v_mul_f32_e32 v158, v235, v158
	v_mul_f32_e32 v159, v235, v159
	v_mul_f32_e32 v160, v235, v160
	v_mul_f32_e32 v161, v235, v161
	v_cvt_pk_bf16_f32 v204, v154, v155
	v_cvt_pk_bf16_f32 v205, v156, v157
	v_cvt_pk_bf16_f32 v206, v158, v159
	v_cvt_pk_bf16_f32 v207, v160, v161
	global_store_dwordx4 v137, v[204:207], s[26:27]
	s_barrier
	s_waitcnt vmcnt(0)
	ds_write_b32 v123, v140 offset:0
	ds_write_b32 v123, v141 offset:4
	ds_write_b32 v123, v142 offset:8
	ds_write_b32 v123, v143 offset:12
	ds_write_b32 v123, v150 offset:8320
	ds_write_b32 v123, v151 offset:8324
	ds_write_b32 v123, v152 offset:8328
	ds_write_b32 v123, v153 offset:8332
	s_waitcnt lgkmcnt(0)
	s_barrier
	s_mov_b64 s[26:27], s[16:17]
	s_add_i32 s4, s2, 1792
	s_and_b32 s3, s4, 15
	s_lshr_b32 s5, s4, 4
	s_mul_i32 s17, s3, 0x220000
	s_lshl_b32 s20, s5, 8
	s_add_i32 s17, s17, s20
	s_add_u32 s6, s28, s17
	s_addc_u32 s7, s29, 0
	s_add_u32 s12, s6, 0x110000
	s_addc_u32 s13, s7, 0
	s_lshl_b32 s17, s5, 17
	s_lshl_b32 s20, s3, 7
	s_add_i32 s17, s17, s20
	s_add_u32 s16, s96, s17
	s_addc_u32 s17, s97, 0
	s_add_u32 s16, s16, 0xf000000
	s_addc_u32 s17, s17, 0
	global_load_dwordx4 v[140:143], v138, s[6:7]
	global_load_dwordx4 v[150:153], v138, s[12:13]
	ds_read_b32 v154, v136 offset:0
	ds_read_b32 v155, v136 offset:260
	ds_read_b32 v156, v136 offset:520
	ds_read_b32 v157, v136 offset:780
	ds_read_b32 v158, v136 offset:1040
	ds_read_b32 v159, v136 offset:1300
	ds_read_b32 v160, v136 offset:1560
	ds_read_b32 v161, v136 offset:1820
	s_waitcnt lgkmcnt(0)
	v_mul_f32_e32 v154, v235, v154
	v_mul_f32_e32 v155, v235, v155
	v_mul_f32_e32 v156, v235, v156
	v_mul_f32_e32 v157, v235, v157
	v_mul_f32_e32 v158, v235, v158
	v_mul_f32_e32 v159, v235, v159
	v_mul_f32_e32 v160, v235, v160
	v_mul_f32_e32 v161, v235, v161
	v_cvt_pk_bf16_f32 v204, v154, v155
	v_cvt_pk_bf16_f32 v205, v156, v157
	v_cvt_pk_bf16_f32 v206, v158, v159
	v_cvt_pk_bf16_f32 v207, v160, v161
	global_store_dwordx4 v137, v[204:207], s[26:27]
	s_barrier
	s_waitcnt vmcnt(0)
	ds_write_b32 v123, v140 offset:0
	ds_write_b32 v123, v141 offset:4
	ds_write_b32 v123, v142 offset:8
	ds_write_b32 v123, v143 offset:12
	ds_write_b32 v123, v150 offset:8320
	ds_write_b32 v123, v151 offset:8324
	ds_write_b32 v123, v152 offset:8328
	ds_write_b32 v123, v153 offset:8332
	s_waitcnt lgkmcnt(0)
	s_barrier
	s_mov_b64 s[26:27], s[16:17]
	s_add_i32 s4, s2, 1920
	s_and_b32 s3, s4, 15
	s_lshr_b32 s5, s4, 4
	s_mul_i32 s17, s3, 0x220000
	s_lshl_b32 s20, s5, 8
	s_add_i32 s17, s17, s20
	s_add_u32 s6, s28, s17
	s_addc_u32 s7, s29, 0
	s_add_u32 s12, s6, 0x110000
	s_addc_u32 s13, s7, 0
	s_lshl_b32 s17, s5, 17
	s_lshl_b32 s20, s3, 7
	s_add_i32 s17, s17, s20
	s_add_u32 s16, s96, s17
	s_addc_u32 s17, s97, 0
	s_add_u32 s16, s16, 0xf000000
	s_addc_u32 s17, s17, 0
	global_load_dwordx4 v[140:143], v138, s[6:7]
	global_load_dwordx4 v[150:153], v138, s[12:13]
	ds_read_b32 v154, v136 offset:0
	ds_read_b32 v155, v136 offset:260
	ds_read_b32 v156, v136 offset:520
	ds_read_b32 v157, v136 offset:780
	ds_read_b32 v158, v136 offset:1040
	ds_read_b32 v159, v136 offset:1300
	ds_read_b32 v160, v136 offset:1560
	ds_read_b32 v161, v136 offset:1820
	s_waitcnt lgkmcnt(0)
	v_mul_f32_e32 v154, v235, v154
	v_mul_f32_e32 v155, v235, v155
	v_mul_f32_e32 v156, v235, v156
	v_mul_f32_e32 v157, v235, v157
	v_mul_f32_e32 v158, v235, v158
	v_mul_f32_e32 v159, v235, v159
	v_mul_f32_e32 v160, v235, v160
	v_mul_f32_e32 v161, v235, v161
	v_cvt_pk_bf16_f32 v204, v154, v155
	v_cvt_pk_bf16_f32 v205, v156, v157
	v_cvt_pk_bf16_f32 v206, v158, v159
	v_cvt_pk_bf16_f32 v207, v160, v161
	global_store_dwordx4 v137, v[204:207], s[26:27]
	s_barrier
	s_waitcnt vmcnt(0)
	ds_write_b32 v123, v140 offset:0
	ds_write_b32 v123, v141 offset:4
	ds_write_b32 v123, v142 offset:8
	ds_write_b32 v123, v143 offset:12
	ds_write_b32 v123, v150 offset:8320
	ds_write_b32 v123, v151 offset:8324
	ds_write_b32 v123, v152 offset:8328
	ds_write_b32 v123, v153 offset:8332
	s_waitcnt lgkmcnt(0)
	s_barrier
	s_mov_b64 s[26:27], s[16:17]
	s_add_i32 s4, s2, 2048
	s_and_b32 s3, s4, 15
	s_lshr_b32 s5, s4, 4
	s_mul_i32 s17, s3, 0x220000
	s_lshl_b32 s20, s5, 8
	s_add_i32 s17, s17, s20
	s_add_u32 s6, s28, s17
	s_addc_u32 s7, s29, 0
	s_add_u32 s12, s6, 0x110000
	s_addc_u32 s13, s7, 0
	s_lshl_b32 s17, s5, 17
	s_lshl_b32 s20, s3, 7
	s_add_i32 s17, s17, s20
	s_add_u32 s16, s96, s17
	s_addc_u32 s17, s97, 0
	s_add_u32 s16, s16, 0xf000000
	s_addc_u32 s17, s17, 0
	global_load_dwordx4 v[140:143], v138, s[6:7]
	global_load_dwordx4 v[150:153], v138, s[12:13]
	ds_read_b32 v154, v136 offset:0
	ds_read_b32 v155, v136 offset:260
	ds_read_b32 v156, v136 offset:520
	ds_read_b32 v157, v136 offset:780
	ds_read_b32 v158, v136 offset:1040
	ds_read_b32 v159, v136 offset:1300
	ds_read_b32 v160, v136 offset:1560
	ds_read_b32 v161, v136 offset:1820
	s_waitcnt lgkmcnt(0)
	v_mul_f32_e32 v154, v235, v154
	v_mul_f32_e32 v155, v235, v155
	v_mul_f32_e32 v156, v235, v156
	v_mul_f32_e32 v157, v235, v157
	v_mul_f32_e32 v158, v235, v158
	v_mul_f32_e32 v159, v235, v159
	v_mul_f32_e32 v160, v235, v160
	v_mul_f32_e32 v161, v235, v161
	v_cvt_pk_bf16_f32 v204, v154, v155
	v_cvt_pk_bf16_f32 v205, v156, v157
	v_cvt_pk_bf16_f32 v206, v158, v159
	v_cvt_pk_bf16_f32 v207, v160, v161
	global_store_dwordx4 v137, v[204:207], s[26:27]
	s_barrier
	s_waitcnt vmcnt(0)
	ds_write_b32 v123, v140 offset:0
	ds_write_b32 v123, v141 offset:4
	ds_write_b32 v123, v142 offset:8
	ds_write_b32 v123, v143 offset:12
	ds_write_b32 v123, v150 offset:8320
	ds_write_b32 v123, v151 offset:8324
	ds_write_b32 v123, v152 offset:8328
	ds_write_b32 v123, v153 offset:8332
	s_waitcnt lgkmcnt(0)
	s_barrier
	s_mov_b64 s[26:27], s[16:17]
	ds_read_b32 v154, v136 offset:0
	ds_read_b32 v155, v136 offset:260
	ds_read_b32 v156, v136 offset:520
	ds_read_b32 v157, v136 offset:780
	ds_read_b32 v158, v136 offset:1040
	ds_read_b32 v159, v136 offset:1300
	ds_read_b32 v160, v136 offset:1560
	ds_read_b32 v161, v136 offset:1820
	s_waitcnt lgkmcnt(0)
	v_mul_f32_e32 v154, v235, v154
	v_mul_f32_e32 v155, v235, v155
	v_mul_f32_e32 v156, v235, v156
	v_mul_f32_e32 v157, v235, v157
	v_mul_f32_e32 v158, v235, v158
	v_mul_f32_e32 v159, v235, v159
	v_mul_f32_e32 v160, v235, v160
	v_mul_f32_e32 v161, v235, v161
	v_cvt_pk_bf16_f32 v204, v154, v155
	v_cvt_pk_bf16_f32 v205, v156, v157
	v_cvt_pk_bf16_f32 v206, v158, v159
	v_cvt_pk_bf16_f32 v207, v160, v161
	global_store_dwordx4 v137, v[204:207], s[26:27]
	s_barrier

.LBB0_775:
	s_add_i32 s23, s23, s98
	s_cmpk_gt_i32 s23, 0x57f
	v_add_u32_e32 v9, 0x2080, v13
	s_cselect_b64 s[6:7], -1, 0
	s_waitcnt vmcnt(1)
	ds_write2_b32 v13, v0, v1 offset1:1
	ds_write2_b32 v13, v2, v3 offset0:2 offset1:3
	s_waitcnt vmcnt(0)
	ds_write2_b32 v9, v4, v5 offset1:1
	v_add_u32_e32 v9, 0x2088, v13
	s_and_b64 vcc, exec, s[6:7]
	ds_write2_b32 v9, v6, v7 offset1:1
	s_waitcnt lgkmcnt(0)
	s_barrier
	s_cbranch_vccnz .LBB0_790
	s_and_b32 s22, s3, 0xffffffc0
	s_cmpk_lt_i32 s22, 0x400
	s_cselect_b64 s[8:9], -1, 0
	s_cmpk_lt_u32 s3, 0x600
	s_cselect_b64 s[12:13], -1, 0
	s_or_b64 s[8:9], s[8:9], s[12:13]
	s_and_b64 vcc, exec, s[8:9]
	s_mov_b32 s11, s22
	s_cbranch_vccnz .LBB0_789
	s_cmpk_gt_u32 s3, 0x8ff
	s_mov_b64 s[8:9], -1
	s_cbranch_scc0 .LBB0_787
	s_cmpk_gt_u32 s3, 0xbff
	s_cbranch_scc0 .LBB0_784
	s_cmpk_gt_u32 s3, 0xeff
	s_cbranch_scc0 .LBB0_781
	s_add_i32 s8, s22, 0xfffff700
	s_cmpk_lt_u32 s3, 0x1200
	s_cselect_b32 s11, s8, s22
	s_mov_b64 s[8:9], 0
